# grid-barrier spin loops without s_sleep (on top of the best version)
# speedup vs baseline: 1.0012x; 1.0011x over previous
; __device__ __forceinline__ unsigned xb_ld(unsigned* p)              { return __hip_atomic_load(p, __ATOMIC_RELAXED, __HIP_MEMORY_SCOPE_AGENT); }
; __device__ __forceinline__ void xcd_barrier_complete(unsigned* bar, unsigned x, unsigned& nloc, unsigned& nx) {
;     ...
;     for (;;) {
;         sum = 0u; cnt = 0u; mine = 0u;
; #pragma unroll
;         for (unsigned j = 0; j < 16; ++j) { const unsigned c = xb_ld(&bar[XB_XCNT(j)]); sum += c; cnt += (c > 0u) ? 1u : 0u; mine = (j == x) ? c : mine; }
;         if (sum == G) break;
;         __builtin_amdgcn_s_sleep(1);
;         if ((++sp & 255u) == 0u) { if (xb_ld(&bar[XB_TMO])) break; if (sp > XB_SPIN_CAP) { atomicAdd(&bar[XB_TMO], 1u); break; } }
;     }
.LBB0_79:
	global_load_dword v16, v17, s[8:9] sc1
	global_load_dword v1, v17, s[14:15] sc1
	global_load_dword v2, v17, s[16:17] sc1
	global_load_dword v3, v17, s[20:21] sc1
	global_load_dword v4, v17, s[38:39] sc1
	global_load_dword v5, v17, s[42:43] sc1
	global_load_dword v6, v17, s[44:45] sc1
	global_load_dword v7, v17, s[46:47] sc1
	global_load_dword v8, v17, s[52:53] sc1
	global_load_dword v9, v17, s[64:65] sc1
	global_load_dword v10, v17, s[70:71] sc1
	global_load_dword v11, v17, s[80:81] sc1
	global_load_dword v12, v17, s[82:83] sc1
	global_load_dword v13, v17, s[84:85] sc1
	global_load_dword v14, v17, s[86:87] sc1
	global_load_dword v15, v17, s[88:89] sc1
	s_mov_b64 s[90:91], -1
	s_mov_b64 s[92:93], -1
	s_waitcnt vmcnt(14)
	v_add_u32_e32 v18, v1, v16
	s_waitcnt vmcnt(13)
	v_add_u32_e32 v18, v18, v2
	s_waitcnt vmcnt(12)
	v_add_u32_e32 v18, v18, v3
	s_waitcnt vmcnt(11)
	v_add_u32_e32 v18, v18, v4
	s_waitcnt vmcnt(10)
	v_add_u32_e32 v18, v18, v5
	s_waitcnt vmcnt(9)
	v_add_u32_e32 v18, v18, v6
	s_waitcnt vmcnt(8)
	v_add_u32_e32 v18, v18, v7
	s_waitcnt vmcnt(7)
	v_add_u32_e32 v18, v18, v8
	s_waitcnt vmcnt(6)
	v_add_u32_e32 v18, v18, v9
	s_waitcnt vmcnt(5)
	v_add_u32_e32 v18, v18, v10
	s_waitcnt vmcnt(4)
	v_add_u32_e32 v18, v18, v11
	s_waitcnt vmcnt(3)
	v_add_u32_e32 v18, v18, v12
	s_waitcnt vmcnt(2)
	v_add_u32_e32 v18, v18, v13
	s_waitcnt vmcnt(1)
	v_add_u32_e32 v18, v18, v14
	s_waitcnt vmcnt(0)
	v_add_u32_e32 v18, v18, v15
	v_cmp_eq_u32_e32 vcc, s3, v18
	s_cbranch_vccnz .LBB0_78
	s_and_b32 s11, s10, 0xff
	s_cmp_eq_u32 s11, 0
	s_mov_b64 s[94:95], -1
	s_cbranch_scc1 .LBB0_83
	s_and_b64 vcc, exec, s[94:95]
	s_cbranch_vccz .LBB0_78

.LBB0_97:
	s_and_b32 s10, s3, 0xff
	s_mov_b64 s[44:45], -1
	s_cmp_lg_u32 s10, 0
	s_mov_b64 s[52:53], -1
	s_cbranch_scc0 .LBB0_100
	s_and_b64 vcc, exec, s[52:53]
	s_cbranch_vccz .LBB0_96

.LBB0_114:
	s_and_b32 s10, s3, 0xff
	s_cmp_lg_u32 s10, 0
	s_mov_b64 s[46:47], -1
	s_cbranch_scc0 .LBB0_117
	s_mov_b64 s[52:53], -1
	s_and_b64 vcc, exec, s[46:47]
	s_cbranch_vccz .LBB0_113

; __device__ __forceinline__ unsigned xb_ld(unsigned* p)              { return __hip_atomic_load(p, __ATOMIC_RELAXED, __HIP_MEMORY_SCOPE_AGENT); }
; __device__ __forceinline__ void xcd_barrier_complete(unsigned* bar, unsigned x, unsigned& nloc, unsigned& nx) {
;     ...
;     for (;;) {
;         sum = 0u; cnt = 0u; mine = 0u;
; #pragma unroll
;         for (unsigned j = 0; j < 16; ++j) { const unsigned c = xb_ld(&bar[XB_XCNT(j)]); sum += c; cnt += (c > 0u) ? 1u : 0u; mine = (j == x) ? c : mine; }
;         if (sum == G) break;
;         __builtin_amdgcn_s_sleep(1);
;         if ((++sp & 255u) == 0u) { if (xb_ld(&bar[XB_TMO])) break; if (sp > XB_SPIN_CAP) { atomicAdd(&bar[XB_TMO], 1u); break; } }
;     }
.LBB0_172:
	global_load_dword v16, v17, s[8:9] sc1
	global_load_dword v1, v17, s[14:15] sc1
	global_load_dword v2, v17, s[16:17] sc1
	global_load_dword v3, v17, s[20:21] sc1
	global_load_dword v4, v17, s[38:39] sc1
	global_load_dword v5, v17, s[40:41] sc1
	global_load_dword v6, v17, s[46:47] sc1
	global_load_dword v7, v17, s[48:49] sc1
	global_load_dword v8, v17, s[50:51] sc1
	global_load_dword v9, v17, s[52:53] sc1
	global_load_dword v10, v17, s[64:65] sc1
	global_load_dword v11, v17, s[66:67] sc1
	global_load_dword v12, v17, s[70:71] sc1
	global_load_dword v13, v17, s[80:81] sc1
	global_load_dword v14, v17, s[82:83] sc1
	global_load_dword v15, v17, s[84:85] sc1
	s_mov_b64 s[86:87], -1
	s_mov_b64 s[88:89], -1
	s_waitcnt vmcnt(14)
	v_add_u32_e32 v18, v1, v16
	s_waitcnt vmcnt(13)
	v_add_u32_e32 v18, v18, v2
	s_waitcnt vmcnt(12)
	v_add_u32_e32 v18, v18, v3
	s_waitcnt vmcnt(11)
	v_add_u32_e32 v18, v18, v4
	s_waitcnt vmcnt(10)
	v_add_u32_e32 v18, v18, v5
	s_waitcnt vmcnt(9)
	v_add_u32_e32 v18, v18, v6
	s_waitcnt vmcnt(8)
	v_add_u32_e32 v18, v18, v7
	s_waitcnt vmcnt(7)
	v_add_u32_e32 v18, v18, v8
	s_waitcnt vmcnt(6)
	v_add_u32_e32 v18, v18, v9
	s_waitcnt vmcnt(5)
	v_add_u32_e32 v18, v18, v10
	s_waitcnt vmcnt(4)
	v_add_u32_e32 v18, v18, v11
	s_waitcnt vmcnt(3)
	v_add_u32_e32 v18, v18, v12
	s_waitcnt vmcnt(2)
	v_add_u32_e32 v18, v18, v13
	s_waitcnt vmcnt(1)
	v_add_u32_e32 v18, v18, v14
	s_waitcnt vmcnt(0)
	v_add_u32_e32 v18, v18, v15
	v_cmp_eq_u32_e32 vcc, s3, v18
	s_cbranch_vccnz .LBB0_171
	s_and_b32 s11, s10, 0xff
	s_cmp_eq_u32 s11, 0
	s_mov_b64 s[90:91], -1
	s_cbranch_scc1 .LBB0_176
	s_and_b64 vcc, exec, s[90:91]
	s_cbranch_vccz .LBB0_171

.LBB0_190:
	s_and_b32 s10, s3, 0xff
	s_mov_b64 s[46:47], -1
	s_cmp_lg_u32 s10, 0
	s_mov_b64 s[50:51], -1
	s_cbranch_scc0 .LBB0_193
	s_and_b64 vcc, exec, s[50:51]
	s_cbranch_vccz .LBB0_189

.LBB0_207:
	s_and_b32 s10, s3, 0xff
	s_cmp_lg_u32 s10, 0
	s_mov_b64 s[48:49], -1
	s_cbranch_scc0 .LBB0_210
	s_mov_b64 s[50:51], -1
	s_and_b64 vcc, exec, s[48:49]
	s_cbranch_vccz .LBB0_206

; __device__ __forceinline__ unsigned xb_ld(unsigned* p)              { return __hip_atomic_load(p, __ATOMIC_RELAXED, __HIP_MEMORY_SCOPE_AGENT); }
; __device__ __forceinline__ void xcd_barrier_complete(unsigned* bar, unsigned x, unsigned& nloc, unsigned& nx) {
;     ...
;     for (;;) {
;         sum = 0u; cnt = 0u; mine = 0u;
; #pragma unroll
;         for (unsigned j = 0; j < 16; ++j) { const unsigned c = xb_ld(&bar[XB_XCNT(j)]); sum += c; cnt += (c > 0u) ? 1u : 0u; mine = (j == x) ? c : mine; }
;         if (sum == G) break;
;         __builtin_amdgcn_s_sleep(1);
;         if ((++sp & 255u) == 0u) { if (xb_ld(&bar[XB_TMO])) break; if (sp > XB_SPIN_CAP) { atomicAdd(&bar[XB_TMO], 1u); break; } }
;     }
.LBB0_477:
	global_load_dword v16, v17, s[8:9] sc1
	global_load_dword v1, v17, s[10:11] sc1
	global_load_dword v2, v17, s[12:13] sc1
	global_load_dword v3, v17, s[14:15] sc1
	global_load_dword v4, v17, s[16:17] sc1
	global_load_dword v5, v17, s[22:23] sc1
	global_load_dword v6, v17, s[40:41] sc1
	global_load_dword v7, v17, s[46:47] sc1
	global_load_dword v8, v17, s[48:49] sc1
	global_load_dword v9, v17, s[50:51] sc1
	global_load_dword v10, v17, s[52:53] sc1
	global_load_dword v11, v17, s[58:59] sc1
	global_load_dword v12, v17, s[64:65] sc1
	global_load_dword v13, v17, s[66:67] sc1
	global_load_dword v14, v17, s[70:71] sc1
	global_load_dword v15, v17, s[80:81] sc1
	s_mov_b64 s[82:83], -1
	s_mov_b64 s[84:85], -1
	s_waitcnt vmcnt(14)
	v_add_u32_e32 v18, v1, v16
	s_waitcnt vmcnt(13)
	v_add_u32_e32 v18, v18, v2
	s_waitcnt vmcnt(12)
	v_add_u32_e32 v18, v18, v3
	s_waitcnt vmcnt(11)
	v_add_u32_e32 v18, v18, v4
	s_waitcnt vmcnt(10)
	v_add_u32_e32 v18, v18, v5
	s_waitcnt vmcnt(9)
	v_add_u32_e32 v18, v18, v6
	s_waitcnt vmcnt(8)
	v_add_u32_e32 v18, v18, v7
	s_waitcnt vmcnt(7)
	v_add_u32_e32 v18, v18, v8
	s_waitcnt vmcnt(6)
	v_add_u32_e32 v18, v18, v9
	s_waitcnt vmcnt(5)
	v_add_u32_e32 v18, v18, v10
	s_waitcnt vmcnt(4)
	v_add_u32_e32 v18, v18, v11
	s_waitcnt vmcnt(3)
	v_add_u32_e32 v18, v18, v12
	s_waitcnt vmcnt(2)
	v_add_u32_e32 v18, v18, v13
	s_waitcnt vmcnt(1)
	v_add_u32_e32 v18, v18, v14
	s_waitcnt vmcnt(0)
	v_add_u32_e32 v18, v18, v15
	v_cmp_eq_u32_e32 vcc, s3, v18
	s_cbranch_vccnz .LBB0_476
	s_and_b32 s34, s19, 0xff
	s_cmp_eq_u32 s34, 0
	s_mov_b64 s[86:87], -1
	s_cbranch_scc1 .LBB0_481
	s_and_b64 vcc, exec, s[86:87]
	s_cbranch_vccz .LBB0_476

.LBB0_495:
	s_and_b32 s19, s3, 0xff
	s_mov_b64 s[40:41], -1
	s_cmp_lg_u32 s19, 0
	s_mov_b64 s[48:49], -1
	s_cbranch_scc0 .LBB0_498
	s_and_b64 vcc, exec, s[48:49]
	s_cbranch_vccz .LBB0_494

.LBB0_512:
	s_and_b32 s19, s3, 0xff
	s_cmp_lg_u32 s19, 0
	s_mov_b64 s[46:47], -1
	s_cbranch_scc0 .LBB0_515
	s_mov_b64 s[48:49], -1
	s_and_b64 vcc, exec, s[46:47]
	s_cbranch_vccz .LBB0_511

; __device__ __forceinline__ unsigned xb_ld(unsigned* p)              { return __hip_atomic_load(p, __ATOMIC_RELAXED, __HIP_MEMORY_SCOPE_AGENT); }
; __device__ __forceinline__ void xcd_barrier_complete(unsigned* bar, unsigned x, unsigned& nloc, unsigned& nx) {
;     ...
;     for (;;) {
;         sum = 0u; cnt = 0u; mine = 0u;
; #pragma unroll
;         for (unsigned j = 0; j < 16; ++j) { const unsigned c = xb_ld(&bar[XB_XCNT(j)]); sum += c; cnt += (c > 0u) ? 1u : 0u; mine = (j == x) ? c : mine; }
;         if (sum == G) break;
;         __builtin_amdgcn_s_sleep(1);
;         if ((++sp & 255u) == 0u) { if (xb_ld(&bar[XB_TMO])) break; if (sp > XB_SPIN_CAP) { atomicAdd(&bar[XB_TMO], 1u); break; } }
;     }
.LBB0_549:
	global_load_dword v16, v17, s[8:9] sc1
	global_load_dword v1, v17, s[10:11] sc1
	global_load_dword v2, v17, s[12:13] sc1
	global_load_dword v3, v17, s[14:15] sc1
	global_load_dword v4, v17, s[16:17] sc1
	global_load_dword v5, v17, s[22:23] sc1
	global_load_dword v6, v17, s[24:25] sc1
	global_load_dword v7, v17, s[40:41] sc1
	global_load_dword v8, v17, s[46:47] sc1
	global_load_dword v9, v17, s[48:49] sc1
	global_load_dword v10, v17, s[50:51] sc1
	global_load_dword v11, v17, s[52:53] sc1
	global_load_dword v12, v17, s[58:59] sc1
	global_load_dword v13, v17, s[64:65] sc1
	global_load_dword v14, v17, s[66:67] sc1
	global_load_dword v15, v17, s[70:71] sc1
	s_mov_b64 s[80:81], -1
	s_mov_b64 s[82:83], -1
	s_waitcnt vmcnt(14)
	v_add_u32_e32 v18, v1, v16
	s_waitcnt vmcnt(13)
	v_add_u32_e32 v18, v18, v2
	s_waitcnt vmcnt(12)
	v_add_u32_e32 v18, v18, v3
	s_waitcnt vmcnt(11)
	v_add_u32_e32 v18, v18, v4
	s_waitcnt vmcnt(10)
	v_add_u32_e32 v18, v18, v5
	s_waitcnt vmcnt(9)
	v_add_u32_e32 v18, v18, v6
	s_waitcnt vmcnt(8)
	v_add_u32_e32 v18, v18, v7
	s_waitcnt vmcnt(7)
	v_add_u32_e32 v18, v18, v8
	s_waitcnt vmcnt(6)
	v_add_u32_e32 v18, v18, v9
	s_waitcnt vmcnt(5)
	v_add_u32_e32 v18, v18, v10
	s_waitcnt vmcnt(4)
	v_add_u32_e32 v18, v18, v11
	s_waitcnt vmcnt(3)
	v_add_u32_e32 v18, v18, v12
	s_waitcnt vmcnt(2)
	v_add_u32_e32 v18, v18, v13
	s_waitcnt vmcnt(1)
	v_add_u32_e32 v18, v18, v14
	s_waitcnt vmcnt(0)
	v_add_u32_e32 v18, v18, v15
	v_cmp_eq_u32_e32 vcc, s3, v18
	s_cbranch_vccnz .LBB0_548
	s_and_b32 s34, s19, 0xff
	s_cmp_eq_u32 s34, 0
	s_mov_b64 s[84:85], -1
	s_cbranch_scc1 .LBB0_553
	s_and_b64 vcc, exec, s[84:85]
	s_cbranch_vccz .LBB0_548

.LBB0_567:
	s_and_b32 s19, s3, 0xff
	s_mov_b64 s[24:25], -1
	s_cmp_lg_u32 s19, 0
	s_mov_b64 s[46:47], -1
	s_cbranch_scc0 .LBB0_570
	s_and_b64 vcc, exec, s[46:47]
	s_cbranch_vccz .LBB0_566

.LBB0_584:
	s_and_b32 s19, s3, 0xff
	s_cmp_lg_u32 s19, 0
	s_mov_b64 s[40:41], -1
	s_cbranch_scc0 .LBB0_587
	s_mov_b64 s[46:47], -1
	s_and_b64 vcc, exec, s[40:41]
	s_cbranch_vccz .LBB0_583

; __device__ __forceinline__ unsigned xb_ld(unsigned* p)              { return __hip_atomic_load(p, __ATOMIC_RELAXED, __HIP_MEMORY_SCOPE_AGENT); }
; __device__ __forceinline__ void xcd_barrier_complete(unsigned* bar, unsigned x, unsigned& nloc, unsigned& nx) {
;     ...
;     for (;;) {
;         sum = 0u; cnt = 0u; mine = 0u;
; #pragma unroll
;         for (unsigned j = 0; j < 16; ++j) { const unsigned c = xb_ld(&bar[XB_XCNT(j)]); sum += c; cnt += (c > 0u) ? 1u : 0u; mine = (j == x) ? c : mine; }
;         if (sum == G) break;
;         __builtin_amdgcn_s_sleep(1);
;         if ((++sp & 255u) == 0u) { if (xb_ld(&bar[XB_TMO])) break; if (sp > XB_SPIN_CAP) { atomicAdd(&bar[XB_TMO], 1u); break; } }
;     }
.LBB0_648:
	global_load_dword v16, v17, s[8:9] sc1
	global_load_dword v1, v17, s[10:11] sc1
	global_load_dword v2, v17, s[12:13] sc1
	global_load_dword v3, v17, s[14:15] sc1
	global_load_dword v4, v17, s[16:17] sc1
	global_load_dword v5, v17, s[22:23] sc1
	global_load_dword v6, v17, s[24:25] sc1
	global_load_dword v7, v17, s[40:41] sc1
	global_load_dword v8, v17, s[46:47] sc1
	global_load_dword v9, v17, s[48:49] sc1
	global_load_dword v10, v17, s[50:51] sc1
	global_load_dword v11, v17, s[52:53] sc1
	global_load_dword v12, v17, s[54:55] sc1
	global_load_dword v13, v17, s[56:57] sc1
	global_load_dword v14, v17, s[58:59] sc1
	global_load_dword v15, v17, s[60:61] sc1
	s_mov_b64 s[62:63], -1
	s_mov_b64 s[64:65], -1
	s_waitcnt vmcnt(14)
	v_add_u32_e32 v18, v1, v16
	s_waitcnt vmcnt(13)
	v_add_u32_e32 v18, v18, v2
	s_waitcnt vmcnt(12)
	v_add_u32_e32 v18, v18, v3
	s_waitcnt vmcnt(11)
	v_add_u32_e32 v18, v18, v4
	s_waitcnt vmcnt(10)
	v_add_u32_e32 v18, v18, v5
	s_waitcnt vmcnt(9)
	v_add_u32_e32 v18, v18, v6
	s_waitcnt vmcnt(8)
	v_add_u32_e32 v18, v18, v7
	s_waitcnt vmcnt(7)
	v_add_u32_e32 v18, v18, v8
	s_waitcnt vmcnt(6)
	v_add_u32_e32 v18, v18, v9
	s_waitcnt vmcnt(5)
	v_add_u32_e32 v18, v18, v10
	s_waitcnt vmcnt(4)
	v_add_u32_e32 v18, v18, v11
	s_waitcnt vmcnt(3)
	v_add_u32_e32 v18, v18, v12
	s_waitcnt vmcnt(2)
	v_add_u32_e32 v18, v18, v13
	s_waitcnt vmcnt(1)
	v_add_u32_e32 v18, v18, v14
	s_waitcnt vmcnt(0)
	v_add_u32_e32 v18, v18, v15
	v_cmp_eq_u32_e32 vcc, s3, v18
	s_cbranch_vccnz .LBB0_647
	s_and_b32 s33, s19, 0xff
	s_cmp_eq_u32 s33, 0
	s_mov_b64 s[66:67], -1
	s_cbranch_scc1 .LBB0_652
	s_and_b64 vcc, exec, s[66:67]
	s_cbranch_vccz .LBB0_647

; __device__ __forceinline__ unsigned xb_ld(unsigned* p)              { return __hip_atomic_load(p, __ATOMIC_RELAXED, __HIP_MEMORY_SCOPE_AGENT); }
; __device__ __forceinline__ void xcd_barrier_complete(unsigned* bar, unsigned x, unsigned& nloc, unsigned& nx) {
;     ...
;     for (;;) {
;         sum = 0u; cnt = 0u; mine = 0u;
; #pragma unroll
;         for (unsigned j = 0; j < 16; ++j) { const unsigned c = xb_ld(&bar[XB_XCNT(j)]); sum += c; cnt += (c > 0u) ? 1u : 0u; mine = (j == x) ? c : mine; }
;         if (sum == G) break;
;         __builtin_amdgcn_s_sleep(1);
;         if ((++sp & 255u) == 0u) { if (xb_ld(&bar[XB_TMO])) break; if (sp > XB_SPIN_CAP) { atomicAdd(&bar[XB_TMO], 1u); break; } }
;     }
.LBB0_741:
	global_load_dword v16, v17, s[8:9] sc1
	global_load_dword v1, v17, s[10:11] sc1
	global_load_dword v2, v17, s[12:13] sc1
	global_load_dword v3, v17, s[14:15] sc1
	global_load_dword v4, v17, s[16:17] sc1
	global_load_dword v5, v17, s[22:23] sc1
	global_load_dword v6, v17, s[24:25] sc1
	global_load_dword v7, v17, s[36:37] sc1
	global_load_dword v8, v17, s[40:41] sc1
	global_load_dword v9, v17, s[46:47] sc1
	global_load_dword v10, v17, s[48:49] sc1
	global_load_dword v11, v17, s[50:51] sc1
	global_load_dword v12, v17, s[52:53] sc1
	global_load_dword v13, v17, s[54:55] sc1
	global_load_dword v14, v17, s[56:57] sc1
	global_load_dword v15, v17, s[58:59] sc1
	s_mov_b64 s[60:61], -1
	s_mov_b64 s[62:63], -1
	s_waitcnt vmcnt(14)
	v_add_u32_e32 v18, v1, v16
	s_waitcnt vmcnt(13)
	v_add_u32_e32 v18, v18, v2
	s_waitcnt vmcnt(12)
	v_add_u32_e32 v18, v18, v3
	s_waitcnt vmcnt(11)
	v_add_u32_e32 v18, v18, v4
	s_waitcnt vmcnt(10)
	v_add_u32_e32 v18, v18, v5
	s_waitcnt vmcnt(9)
	v_add_u32_e32 v18, v18, v6
	s_waitcnt vmcnt(8)
	v_add_u32_e32 v18, v18, v7
	s_waitcnt vmcnt(7)
	v_add_u32_e32 v18, v18, v8
	s_waitcnt vmcnt(6)
	v_add_u32_e32 v18, v18, v9
	s_waitcnt vmcnt(5)
	v_add_u32_e32 v18, v18, v10
	s_waitcnt vmcnt(4)
	v_add_u32_e32 v18, v18, v11
	s_waitcnt vmcnt(3)
	v_add_u32_e32 v18, v18, v12
	s_waitcnt vmcnt(2)
	v_add_u32_e32 v18, v18, v13
	s_waitcnt vmcnt(1)
	v_add_u32_e32 v18, v18, v14
	s_waitcnt vmcnt(0)
	v_add_u32_e32 v18, v18, v15
	v_cmp_eq_u32_e32 vcc, s3, v18
	s_cbranch_vccnz .LBB0_740
	s_and_b32 s33, s19, 0xff
	s_cmp_eq_u32 s33, 0
	s_mov_b64 s[64:65], -1
	s_cbranch_scc1 .LBB0_745
	s_and_b64 vcc, exec, s[64:65]
	s_cbranch_vccz .LBB0_740

.LBB0_759:
	s_and_b32 s19, s3, 0xff
	s_mov_b64 s[24:25], -1
	s_cmp_lg_u32 s19, 0
	s_mov_b64 s[40:41], -1
	s_cbranch_scc0 .LBB0_762
	s_and_b64 vcc, exec, s[40:41]
	s_cbranch_vccz .LBB0_758

.LBB0_776:
	s_and_b32 s19, s3, 0xff
	s_cmp_lg_u32 s19, 0
	s_mov_b64 s[36:37], -1
	s_cbranch_scc0 .LBB0_779
	s_mov_b64 s[40:41], -1
	s_and_b64 vcc, exec, s[36:37]
	s_cbranch_vccz .LBB0_775

; __device__ __forceinline__ unsigned xb_ld(unsigned* p)              { return __hip_atomic_load(p, __ATOMIC_RELAXED, __HIP_MEMORY_SCOPE_AGENT); }
; __device__ __forceinline__ void xcd_barrier_complete(unsigned* bar, unsigned x, unsigned& nloc, unsigned& nx) {
;     ...
;     for (;;) {
;         sum = 0u; cnt = 0u; mine = 0u;
; #pragma unroll
;         for (unsigned j = 0; j < 16; ++j) { const unsigned c = xb_ld(&bar[XB_XCNT(j)]); sum += c; cnt += (c > 0u) ? 1u : 0u; mine = (j == x) ? c : mine; }
;         if (sum == G) break;
;         __builtin_amdgcn_s_sleep(1);
;         if ((++sp & 255u) == 0u) { if (xb_ld(&bar[XB_TMO])) break; if (sp > XB_SPIN_CAP) { atomicAdd(&bar[XB_TMO], 1u); break; } }
;     }
.LBB0_819:
	global_load_dword v16, v17, s[6:7] sc1
	global_load_dword v1, v17, s[8:9] sc1
	global_load_dword v2, v17, s[10:11] sc1
	global_load_dword v3, v17, s[12:13] sc1
	global_load_dword v4, v17, s[14:15] sc1
	global_load_dword v5, v17, s[16:17] sc1
	global_load_dword v6, v17, s[22:23] sc1
	global_load_dword v7, v17, s[24:25] sc1
	global_load_dword v8, v17, s[36:37] sc1
	global_load_dword v9, v17, s[40:41] sc1
	global_load_dword v10, v17, s[42:43] sc1
	global_load_dword v11, v17, s[44:45] sc1
	global_load_dword v12, v17, s[46:47] sc1
	global_load_dword v13, v17, s[48:49] sc1
	global_load_dword v14, v17, s[50:51] sc1
	global_load_dword v15, v17, s[52:53] sc1
	s_mov_b64 s[54:55], -1
	s_mov_b64 s[56:57], -1
	s_waitcnt vmcnt(14)
	v_add_u32_e32 v18, v1, v16
	s_waitcnt vmcnt(13)
	v_add_u32_e32 v18, v18, v2
	s_waitcnt vmcnt(12)
	v_add_u32_e32 v18, v18, v3
	s_waitcnt vmcnt(11)
	v_add_u32_e32 v18, v18, v4
	s_waitcnt vmcnt(10)
	v_add_u32_e32 v18, v18, v5
	s_waitcnt vmcnt(9)
	v_add_u32_e32 v18, v18, v6
	s_waitcnt vmcnt(8)
	v_add_u32_e32 v18, v18, v7
	s_waitcnt vmcnt(7)
	v_add_u32_e32 v18, v18, v8
	s_waitcnt vmcnt(6)
	v_add_u32_e32 v18, v18, v9
	s_waitcnt vmcnt(5)
	v_add_u32_e32 v18, v18, v10
	s_waitcnt vmcnt(4)
	v_add_u32_e32 v18, v18, v11
	s_waitcnt vmcnt(3)
	v_add_u32_e32 v18, v18, v12
	s_waitcnt vmcnt(2)
	v_add_u32_e32 v18, v18, v13
	s_waitcnt vmcnt(1)
	v_add_u32_e32 v18, v18, v14
	s_waitcnt vmcnt(0)
	v_add_u32_e32 v18, v18, v15
	v_cmp_eq_u32_e32 vcc, s3, v18
	s_cbranch_vccnz .LBB0_818
	s_and_b32 s33, s19, 0xff
	s_cmp_eq_u32 s33, 0
	s_mov_b64 s[58:59], -1
	s_cbranch_scc1 .LBB0_823
	s_and_b64 vcc, exec, s[58:59]
	s_cbranch_vccz .LBB0_818

.LBB0_837:
	s_and_b32 s19, s3, 0xff
	s_mov_b64 s[22:23], -1
	s_cmp_lg_u32 s19, 0
	s_mov_b64 s[36:37], -1
	s_cbranch_scc0 .LBB0_840
	s_and_b64 vcc, exec, s[36:37]
	s_cbranch_vccz .LBB0_836

.LBB0_854:
	s_and_b32 s19, s3, 0xff
	s_cmp_lg_u32 s19, 0
	s_mov_b64 s[24:25], -1
	s_cbranch_scc0 .LBB0_857
	s_mov_b64 s[36:37], -1
	s_and_b64 vcc, exec, s[24:25]
	s_cbranch_vccz .LBB0_853
